# v30 + attention branch phase: V fragment reads for both output halves issued together (one LDS wait per pair instead of per MFMA)
# speedup vs baseline: 1.0037x; 1.0037x over previous
; #define LAS __attribute__((address_space(3)))
; __device__ __forceinline__ int tpos(int t) { return (t & ~2047) | ((t & 15) << 7) | ((t & 2047) >> 4); }
; __device__ __forceinline__ void attn_load(const bf16_t* proj, const AttnItem& t, u32x4 (&kv)[6], u32x4 (&vv)[6], int tid) {
;     const int nb0 = t.nb & ~1;
;     const bf16_t* kb = proj + (size_t)NB * NH * SEQ * HD + (size_t)(t.b * NH + t.h) * SEQ * 2 * HD;
; #pragma unroll
;     for (int c = 0; c < 6; ++c) { const int idx = tid + 512 * c, j = idx >> 3, ch = idx & 7; const int sidx = (nb0 - 1) * 128 + j;
;         const int sj = sidx >= 0 ? sidx : sidx + 128;
;         const bf16_t* p = kb + (size_t)tpos(sj * t.dil + t.r) * 2 * HD + ch * 8; kv[c] = *(const u32x4*)p; vv[c] = *(const u32x4*)(p + HD); }
; }
; template <int T0, int NT, bool FIRST>
; __device__ __forceinline__ void attn_group(LAS const unsigned char* Kl, LAS const unsigned char* Vl, const bf16x8 (&qf)[4], f32x16 (&o)[2], float& mx, float& l, int nb, int w, int lane) {
;     const int r32 = lane & 31, hi = lane >> 5;
;     f32x16 s[NT];
; #pragma unroll
;     for (int t = 0; t < NT; ++t) { const float z = (T0 + t < 4 && nb == 0 && w + T0 + t < 4) ? NEGBIG : 0.f;
;         s[t] = (f32x16){z, z, z, z, z, z, z, z, z, z, z, z, z, z, z, z}; }
;     {
;         LAS const unsigned char* kp = Kl + (32 * (w + T0) + r32) * 128;
;         const int sw = (r32 >> 1) & 7;
; #pragma unroll
;         for (int ks = 0; ks < 4; ++ks) {
;             bf16x8 kf[NT];
; #pragma unroll
;             for (int t = 0; t < NT; ++t) kf[t] = *(LAS const bf16x8*)(kp + t * 4096 + (((2 * ks + hi) ^ sw) * 16));
; #pragma unroll
;             for (int t = 0; t < NT; ++t) s[t] = __builtin_amdgcn_mfma_f32_32x32x16_bf16(kf[t], qf[ks], s[t], 0, 0, 0);
;         }
.LBB0_112:
	s_lshl_b32 s2, s7, 1
	s_ashr_i32 s48, s19, 11
	s_add_i32 s19, s2, s18
	s_and_b32 s6, s19, 63
	s_cmpk_lt_u32 s19, 0x800
	s_cselect_b64 s[46:47], -1, 0
	s_and_b64 s[2:3], s[46:47], exec
	s_cselect_b32 s7, 15, 3
	s_cselect_b32 s2, 4, 2
	s_cselect_b32 s3, 2, 4
	s_and_b32 s15, s7, s19
	s_lshl_b32 s49, s15, 7
	s_lshr_b32 s98, s6, s2
	s_and_b32 s6, s49, 0x700
	s_add_i32 s7, s6, 0xffffff80
	v_add_u32_e32 v2, s7, v132
	v_add_u32_e32 v3, s6, v132
	v_cmp_gt_i32_e32 vcc, 0, v2
	s_bfe_u32 s99, s19, 0x20009
	s_bfe_u32 s11, s19, 0x30006
	v_cndmask_b32_e32 v2, v2, v3, vcc
	v_lshlrev_b32_e32 v2, s3, v2
	v_add_u32_e32 v2, s98, v2
	v_lshlrev_b32_e32 v4, 7, v2
	s_lshl_b32 s2, s99, 3
	v_and_b32_e32 v3, 0xfffff800, v2
	v_and_b32_e32 v4, 0x780, v4
	v_bfe_u32 v2, v2, 4, 7
	s_or_b32 s2, s2, s11
	v_or3_b32 v2, v4, v3, v2
	s_lshl_b32 s12, s2, 21
	v_ashrrev_i32_e32 v3, 31, v2
	v_lshl_add_u64 v[0:1], v[130:131], 0, s[12:13]
	v_lshlrev_b64 v[2:3], 8, v[2:3]
	v_lshl_add_u64 v[2:3], v[0:1], 0, v[2:3]
	global_load_dwordx4 v[64:67], v[2:3], off
	global_load_dwordx4 v[68:71], v[2:3], off offset:128
	v_add_u32_e32 v2, s7, v133
	v_add_u32_e32 v3, s6, v133
	v_cmp_gt_i32_e32 vcc, 0, v2
	s_cmp_eq_u32 s25, 0
	v_add_u32_e32 v40, v138, v139
	v_cndmask_b32_e32 v2, v2, v3, vcc
	v_lshlrev_b32_e32 v2, s3, v2
	v_add_u32_e32 v2, s98, v2
	v_lshlrev_b32_e32 v4, 7, v2
	v_and_b32_e32 v3, 0xfffff800, v2
	v_and_b32_e32 v4, 0x780, v4
	v_bfe_u32 v2, v2, 4, 7
	v_or3_b32 v2, v4, v3, v2
	v_ashrrev_i32_e32 v3, 31, v2
	v_lshlrev_b64 v[2:3], 8, v[2:3]
	v_lshl_add_u64 v[2:3], v[0:1], 0, v[2:3]
	global_load_dwordx4 v[72:75], v[2:3], off
	global_load_dwordx4 v[76:79], v[2:3], off offset:128
	v_add_u32_e32 v2, s7, v134
	v_add_u32_e32 v3, s6, v134
	v_cmp_gt_i32_e32 vcc, 0, v2
	v_add_u32_e32 v56, v138, v140
	v_add_u32_e32 v196, v143, v144
	v_cndmask_b32_e32 v2, v2, v3, vcc
	v_lshlrev_b32_e32 v2, s3, v2
	v_add_u32_e32 v2, s98, v2
	v_lshlrev_b32_e32 v4, 7, v2
	v_and_b32_e32 v3, 0xfffff800, v2
	v_and_b32_e32 v4, 0x780, v4
	v_bfe_u32 v2, v2, 4, 7
	v_or3_b32 v2, v4, v3, v2
	v_ashrrev_i32_e32 v3, 31, v2
	v_lshlrev_b64 v[2:3], 8, v[2:3]
	v_lshl_add_u64 v[2:3], v[0:1], 0, v[2:3]
	global_load_dwordx4 v[80:83], v[2:3], off
	global_load_dwordx4 v[84:87], v[2:3], off offset:128
	v_add_u32_e32 v2, s7, v135
	v_add_u32_e32 v3, s6, v135
	v_cmp_gt_i32_e32 vcc, 0, v2
	v_add_u32_e32 v197, v143, v145
	s_nop 0
	v_cndmask_b32_e32 v2, v2, v3, vcc
	v_lshlrev_b32_e32 v2, s3, v2
	v_add_u32_e32 v2, s98, v2
	v_lshlrev_b32_e32 v4, 7, v2
	v_and_b32_e32 v3, 0xfffff800, v2
	v_and_b32_e32 v4, 0x780, v4
	v_bfe_u32 v2, v2, 4, 7
	v_or3_b32 v2, v4, v3, v2
	v_ashrrev_i32_e32 v3, 31, v2
	v_lshlrev_b64 v[2:3], 8, v[2:3]
	v_lshl_add_u64 v[2:3], v[0:1], 0, v[2:3]
	global_load_dwordx4 v[88:91], v[2:3], off
	global_load_dwordx4 v[92:95], v[2:3], off offset:128
	v_add_u32_e32 v2, s7, v136
	v_add_u32_e32 v3, s6, v136
	v_cmp_gt_i32_e32 vcc, 0, v2
	s_nop 1
	v_cndmask_b32_e32 v2, v2, v3, vcc
	v_lshlrev_b32_e32 v2, s3, v2
	v_add_u32_e32 v2, s98, v2
	v_lshlrev_b32_e32 v4, 7, v2
	v_and_b32_e32 v3, 0xfffff800, v2
	v_and_b32_e32 v4, 0x780, v4
	v_bfe_u32 v2, v2, 4, 7
	v_or3_b32 v2, v4, v3, v2
	v_ashrrev_i32_e32 v3, 31, v2
	v_lshlrev_b64 v[2:3], 8, v[2:3]
	v_lshl_add_u64 v[2:3], v[0:1], 0, v[2:3]
	global_load_dwordx4 v[96:99], v[2:3], off
	global_load_dwordx4 v[100:103], v[2:3], off offset:128
	v_add_u32_e32 v2, s7, v137
	v_add_u32_e32 v3, s6, v137
	v_cmp_gt_i32_e32 vcc, 0, v2
	s_cselect_b64 s[6:7], -1, 0
	s_or_b32 s10, s25, s26
	v_cndmask_b32_e32 v2, v2, v3, vcc
	v_lshlrev_b32_e32 v2, s3, v2
	v_add_u32_e32 v2, s98, v2
	v_lshlrev_b32_e32 v4, 7, v2
	v_and_b32_e32 v3, 0xfffff800, v2
	v_and_b32_e32 v4, 0x780, v4
	v_bfe_u32 v2, v2, 4, 7
	v_or3_b32 v2, v4, v3, v2
	v_ashrrev_i32_e32 v3, 31, v2
	v_lshlrev_b64 v[2:3], 8, v[2:3]
	v_readlane_b32 vcc_lo, v250, 4
	v_lshl_add_u64 v[0:1], v[0:1], 0, v[2:3]
	v_readlane_b32 vcc_hi, v250, 5
	global_load_dwordx4 v[104:107], v[0:1], off
	global_load_dwordx4 v[108:111], v[0:1], off offset:128
	s_and_b64 vcc, s[6:7], vcc
	ds_read_b128 v[32:35], v40
	ds_read_b128 v[36:39], v40 offset:4096
	ds_read_b128 v[40:43], v40 offset:8192
	s_cmp_eq_u32 s10, 0
	v_cndmask_b32_e32 v16, 0, v227, vcc
	s_cselect_b64 vcc, -1, 0
	v_cndmask_b32_e32 v0, 0, v227, vcc
	v_mov_b32_e32 v17, v16
	v_mov_b32_e32 v18, v16
	v_mov_b32_e32 v19, v16
	v_mov_b32_e32 v20, v16
	v_mov_b32_e32 v21, v16
	v_mov_b32_e32 v22, v16
	v_mov_b32_e32 v23, v16
	v_mov_b32_e32 v24, v16
	v_mov_b32_e32 v25, v16
	v_mov_b32_e32 v26, v16
	v_mov_b32_e32 v27, v16
	v_mov_b32_e32 v28, v16
	v_mov_b32_e32 v29, v16
	v_mov_b32_e32 v30, v16
	v_mov_b32_e32 v31, v16
	v_mov_b32_e32 v1, v0
	v_mov_b32_e32 v2, v0
	v_mov_b32_e32 v3, v0
	v_mov_b32_e32 v4, v0
	v_mov_b32_e32 v5, v0
	v_mov_b32_e32 v6, v0
	v_mov_b32_e32 v7, v0
	v_mov_b32_e32 v8, v0
	v_mov_b32_e32 v9, v0
	v_mov_b32_e32 v10, v0
	v_mov_b32_e32 v11, v0
	v_mov_b32_e32 v12, v0
	v_mov_b32_e32 v13, v0
	v_mov_b32_e32 v14, v0
	v_mov_b32_e32 v15, v0
	s_waitcnt vmcnt(15) lgkmcnt(2)
	v_mfma_f32_32x32x16_bf16 v[16:31], v[32:35], v[124:127], v[16:31]
	ds_read_b128 v[48:51], v56
	ds_read_b128 v[52:55], v56 offset:4096
	ds_read_b128 v[56:59], v56 offset:8192
	v_readlane_b32 vcc_lo, v250, 6
	v_readlane_b32 vcc_hi, v250, 7
	s_lshl_b32 s2, s2, 20
	s_waitcnt lgkmcnt(4)
	v_mfma_f32_32x32x16_bf16 v[0:15], v[36:39], v[124:127], v[0:15]
	s_waitcnt lgkmcnt(3)
	v_mfma_f32_32x32x16_bf16 v[32:47], v[40:43], v[124:127], 0
	s_waitcnt vmcnt(14) lgkmcnt(0)
	v_mfma_f32_32x32x16_bf16 v[32:47], v[56:59], v[120:123], v[32:47]
	v_add_u32_e32 v56, v138, v141
	v_mfma_f32_32x32x16_bf16 v[16:31], v[48:51], v[120:123], v[16:31]
	v_mfma_f32_32x32x16_bf16 v[0:15], v[52:55], v[120:123], v[0:15]
	ds_read_b128 v[48:51], v56
	ds_read_b128 v[52:55], v56 offset:4096
	ds_read_b128 v[56:59], v56 offset:8192
	s_waitcnt vmcnt(13) lgkmcnt(0)
; __device__ __forceinline__ int crow(int i, int hi) { return (i & 3) + 8 * (i >> 2) + 4 * hi; }
; template <int T0, int NT, bool FIRST>
; __device__ __forceinline__ void attn_group(LAS const unsigned char* Kl, LAS const unsigned char* Vl, const bf16x8 (&qf)[4], f32x16 (&o)[2], float& mx, float& l, int nb, int w, int lane) {
;     ...
; #pragma unroll
;     for (int t = 0; t < NT; ++t) {
;         const int tt = T0 + t;
;         if (tt == 0) {
; #pragma unroll
;             for (int i = 0; i < 16; ++i) if (crow(i, hi) < r32) s[t][i] = NEGBIG; }
;         if (tt == 4) {
; #pragma unroll
;             for (int i = 0; i < 16; ++i) if (crow(i, hi) > r32) s[t][i] = NEGBIG; }
;     }
;     float m0 = s[0][0], m1 = s[0][1], m2 = s[0][2], m3 = s[0][3];
; #pragma unroll
;     for (int t = 0; t < NT; ++t)
; #pragma unroll
;         for (int i = 0; i < 16; i += 4) { m0 = fmaxf(m0, s[t][i]); m1 = fmaxf(m1, s[t][i + 1]); m2 = fmaxf(m2, s[t][i + 2]); m3 = fmaxf(m3, s[t][i + 3]); }
;     float gm = fmaxf(fmaxf(m0, m1), fmaxf(m2, m3));
;     gm = fmaxf(gm, __shfl_xor(gm, 32));
;     if (FIRST) mx = gm;
;     else { const float mn = fmaxf(mx, gm); const float f = __builtin_amdgcn_exp2f(mx - mn); l *= f; mx = mn;
; #pragma unroll
;         for (int d = 0; d < 2; ++d)
; #pragma unroll
;             for (int i = 0; i < 16; ++i) o[d][i] *= f; }
;     float l0 = 0.f, l1 = 0.f, l2 = 0.f, l3 = 0.f;
; #pragma unroll
;     for (int t = 0; t < NT; ++t)
; #pragma unroll
;         for (int i = 0; i < 16; i += 4) {
;             const float p0 = __builtin_amdgcn_exp2f(s[t][i] - mx), p1 = __builtin_amdgcn_exp2f(s[t][i + 1] - mx), p2 = __builtin_amdgcn_exp2f(s[t][i + 2] - mx), p3 = __builtin_amdgcn_exp2f(s[t][i + 3] - mx);
;             s[t][i] = p0; s[t][i + 1] = p1; s[t][i + 2] = p2; s[t][i + 3] = p3; l0 += p0; l1 += p1; l2 += p2; l3 += p3; }
	v_mfma_f32_32x32x16_bf16 v[32:47], v[56:59], v[116:119], v[32:47]
	v_add_u32_e32 v56, v138, v142
	v_mfma_f32_32x32x16_bf16 v[16:31], v[48:51], v[116:119], v[16:31]
	v_mfma_f32_32x32x16_bf16 v[0:15], v[52:55], v[116:119], v[0:15]
	ds_read_b128 v[48:51], v56
	ds_read_b128 v[52:55], v56 offset:4096
	ds_read_b128 v[56:59], v56 offset:8192
	s_waitcnt vmcnt(12) lgkmcnt(0)
	v_mfma_f32_32x32x16_bf16 v[32:47], v[56:59], v[112:115], v[32:47]
	v_mfma_f32_32x32x16_bf16 v[16:31], v[48:51], v[112:115], v[16:31]
	s_nop 10
	v_cndmask_b32_e32 v48, v32, v227, vcc
	v_readlane_b32 vcc_lo, v250, 8
	v_readlane_b32 vcc_hi, v250, 9
	v_cndmask_b32_e64 v32, v48, v32, s[40:41]
	v_cndmask_b32_e64 v33, v227, v33, s[40:41]
	v_cndmask_b32_e32 v34, v34, v227, vcc
	v_readlane_b32 vcc_lo, v250, 10
	v_readlane_b32 vcc_hi, v250, 11
	v_mfma_f32_32x32x16_bf16 v[0:15], v[52:55], v[112:115], v[0:15]
	v_max_f32_e32 v48, v20, v20
	v_cndmask_b32_e32 v35, v35, v227, vcc
	v_readlane_b32 vcc_lo, v250, 12
	v_readlane_b32 vcc_hi, v250, 13
	v_max_f32_e32 v49, v16, v16
	v_max_f32_e32 v48, v49, v48
	v_cndmask_b32_e32 v36, v36, v227, vcc
	v_readlane_b32 vcc_lo, v250, 14
	v_readlane_b32 vcc_hi, v250, 15
	v_max_f32_e32 v49, v21, v21
	v_max_f32_e32 v50, v17, v17
	v_cndmask_b32_e32 v37, v37, v227, vcc
	v_readlane_b32 vcc_lo, v250, 16
	v_readlane_b32 vcc_hi, v250, 17
	v_max_f32_e32 v49, v50, v49
	v_max_f32_e32 v50, v23, v23
	v_cndmask_b32_e32 v38, v38, v227, vcc
	v_readlane_b32 vcc_lo, v250, 18
	v_readlane_b32 vcc_hi, v250, 19
	v_max_f32_e32 v51, v19, v19
	v_max_f32_e32 v50, v51, v50
	v_cndmask_b32_e32 v39, v39, v227, vcc
	v_readlane_b32 vcc_lo, v250, 20
	v_readlane_b32 vcc_hi, v250, 21
	v_max3_f32 v51, v18, v22, v26
	v_max3_f32 v50, v50, v27, v31
	v_cndmask_b32_e32 v40, v40, v227, vcc
	v_readlane_b32 vcc_lo, v250, 22
	v_readlane_b32 vcc_hi, v250, 23
	v_max3_f32 v48, v48, v24, v28
	v_max3_f32 v49, v49, v25, v29
	v_cndmask_b32_e32 v41, v41, v227, vcc
	v_readlane_b32 vcc_lo, v250, 24
	v_readlane_b32 vcc_hi, v250, 25
	v_max3_f32 v51, v51, v30, v2
	v_max3_f32 v50, v50, v3, v7
	v_cndmask_b32_e32 v42, v42, v227, vcc
	v_readlane_b32 vcc_lo, v250, 26
	v_readlane_b32 vcc_hi, v250, 27
	v_max3_f32 v48, v48, v0, v4
	v_max3_f32 v49, v49, v1, v5
	v_cndmask_b32_e32 v43, v43, v227, vcc
	v_readlane_b32 vcc_lo, v250, 28
	v_max3_f32 v51, v51, v6, v10
	v_max3_f32 v50, v50, v11, v15
	v_readlane_b32 vcc_hi, v250, 29
	v_cndmask_b32_e64 v47, v47, v227, s[68:69]
	v_max3_f32 v48, v48, v8, v12
	v_max3_f32 v49, v49, v9, v13
	v_max3_f32 v51, v51, v14, v34
	v_max3_f32 v50, v50, v35, v39
	v_cndmask_b32_e32 v44, v44, v227, vcc
	v_cndmask_b32_e64 v45, v45, v227, s[64:65]
	v_cndmask_b32_e64 v46, v46, v227, s[66:67]
	v_max3_f32 v48, v48, v32, v36
	v_max3_f32 v49, v49, v33, v37
	v_max3_f32 v51, v51, v38, v42
	v_max3_f32 v50, v50, v43, v47
	v_max3_f32 v48, v48, v40, v44
	v_max3_f32 v49, v49, v41, v45
	v_max3_f32 v50, v51, v46, v50
	v_max3_f32 v48, v48, v49, v50
	ds_bpermute_b32 v49, v150, v48
	s_waitcnt lgkmcnt(0)
	v_max_f32_e32 v49, v49, v49
	v_max_f32_e32 v163, v48, v49
	v_sub_f32_e32 v4, v4, v163
	v_exp_f32_e32 v60, v4
	v_sub_f32_e32 v4, v5, v163
	v_exp_f32_e32 v61, v4
	v_sub_f32_e32 v4, v6, v163
	v_exp_f32_e32 v62, v4
	v_sub_f32_e32 v4, v7, v163
	v_exp_f32_e32 v63, v4
	v_sub_f32_e32 v4, v8, v163
	v_exp_f32_e32 v165, v4
	v_sub_f32_e32 v4, v9, v163
	v_exp_f32_e32 v166, v4
	v_sub_f32_e32 v4, v10, v163
	v_exp_f32_e32 v167, v4
	v_sub_f32_e32 v4, v11, v163
	v_exp_f32_e32 v168, v4
	v_sub_f32_e32 v4, v12, v163
	v_exp_f32_e32 v183, v4
	v_sub_f32_e32 v4, v13, v163
	v_sub_f32_e32 v16, v16, v163
	v_exp_f32_e32 v185, v4
	v_sub_f32_e32 v4, v14, v163
	v_exp_f32_e32 v16, v16
	v_sub_f32_e32 v17, v17, v163
	v_sub_f32_e32 v20, v20, v163
	v_exp_f32_e32 v186, v4
	v_sub_f32_e32 v4, v15, v163
	v_exp_f32_e32 v17, v17
	v_sub_f32_e32 v18, v18, v163
	v_exp_f32_e32 v20, v20
	v_sub_f32_e32 v21, v21, v163
	v_sub_f32_e32 v24, v24, v163
	v_exp_f32_e32 v187, v4
	v_sub_f32_e32 v4, v32, v163
	v_exp_f32_e32 v18, v18
	v_sub_f32_e32 v19, v19, v163
	v_exp_f32_e32 v21, v21
	v_sub_f32_e32 v22, v22, v163
	v_exp_f32_e32 v52, v24
	v_sub_f32_e32 v24, v25, v163
	v_exp_f32_e32 v188, v4
	v_sub_f32_e32 v4, v33, v163
	v_exp_f32_e32 v19, v19
	v_exp_f32_e32 v22, v22
	v_sub_f32_e32 v23, v23, v163
	v_exp_f32_e32 v53, v24
	v_sub_f32_e32 v24, v26, v163
	v_exp_f32_e32 v189, v4
	v_sub_f32_e32 v4, v34, v163
	v_add_f32_e32 v48, 0, v16
	v_exp_f32_e32 v23, v23
	v_exp_f32_e32 v54, v24
	v_sub_f32_e32 v24, v27, v163
	v_exp_f32_e32 v190, v4
	v_sub_f32_e32 v4, v35, v163
	v_add_f32_e32 v49, 0, v17
	v_add_f32_e32 v48, v20, v48
	v_exp_f32_e32 v55, v24
	v_sub_f32_e32 v28, v28, v163
	v_exp_f32_e32 v191, v4
	v_sub_f32_e32 v4, v36, v163
	v_add_f32_e32 v50, 0, v18
	v_add_f32_e32 v49, v21, v49
	v_add_f32_e32 v24, v52, v48
	v_exp_f32_e32 v48, v28
	v_sub_f32_e32 v28, v29, v163
	v_sub_f32_e32 v0, v0, v163
	v_exp_f32_e32 v192, v4
	v_sub_f32_e32 v4, v37, v163
	v_add_f32_e32 v51, 0, v19
	v_add_f32_e32 v50, v22, v50
	v_add_f32_e32 v25, v53, v49
	v_exp_f32_e32 v49, v28
	v_sub_f32_e32 v28, v30, v163
	v_exp_f32_e32 v56, v0
	v_sub_f32_e32 v0, v1, v163
	v_exp_f32_e32 v193, v4
	v_sub_f32_e32 v4, v38, v163
	v_add_f32_e32 v51, v23, v51
	v_add_f32_e32 v26, v54, v50
	v_exp_f32_e32 v50, v28
	v_sub_f32_e32 v28, v31, v163
	v_exp_f32_e32 v57, v0
	v_sub_f32_e32 v0, v2, v163
	v_exp_f32_e32 v194, v4
	v_sub_f32_e32 v4, v39, v163
	v_add_f32_e32 v27, v55, v51
	v_exp_f32_e32 v51, v28
	v_exp_f32_e32 v58, v0
	v_sub_f32_e32 v0, v3, v163
	v_exp_f32_e32 v195, v4
	v_sub_f32_e32 v4, v40, v163
	v_exp_f32_e32 v59, v0
	v_exp_f32_e32 v40, v4
	v_sub_f32_e32 v4, v41, v163
	v_exp_f32_e32 v41, v4
	v_sub_f32_e32 v4, v42, v163
	v_exp_f32_e32 v42, v4
; #define LAS __attribute__((address_space(3)))
; __device__ __forceinline__ s16x4 vtr(LAS const unsigned char* p) { return __builtin_bit_cast(s16x4, __builtin_amdgcn_ds_read_tr16_b64_v4i16((LAS v4i16_t*)p)); }
; template <int T0, int NT, bool FIRST>
; __device__ __forceinline__ void attn_group(LAS const unsigned char* Kl, LAS const unsigned char* Vl, const bf16x8 (&qf)[4], f32x16 (&o)[2], float& mx, float& l, int nb, int w, int lane) {
;     ...
;     f32x16 s[NT];
; #pragma unroll
;     for (int t = 0; t < NT; ++t) { const float z = (T0 + t < 4 && nb == 0 && w + T0 + t < 4) ? NEGBIG : 0.f;
;         s[t] = (f32x16){z, z, z, z, z, z, z, z, z, z, z, z, z, z, z, z}; }
;     {
;         LAS const unsigned char* kp = Kl + (32 * (w + T0) + r32) * 128;
;         const int sw = (r32 >> 1) & 7;
; #pragma unroll
;         for (int ks = 0; ks < 4; ++ks) {
;             bf16x8 kf[NT];
; #pragma unroll
;             for (int t = 0; t < NT; ++t) kf[t] = *(LAS const bf16x8*)(kp + t * 4096 + (((2 * ks + hi) ^ sw) * 16));
; #pragma unroll
;             for (int t = 0; t < NT; ++t) s[t] = __builtin_amdgcn_mfma_f32_32x32x16_bf16(kf[t], qf[ks], s[t], 0, 0, 0);
;         }
;     ...
;     const int i16 = lane & 15, q4 = i16 >> 2, p4 = i16 & 3, blk = (lane >> 4) & 1;
;     LAS const unsigned char* vb = Vl + (32 * (w + T0) + 4 * hi + q4) * 128 + 32 * blk + 8 * p4;
;     const int vsw = ((q4 >> 1) & 1) * 64;
; #pragma unroll
;     for (int t = 0; t < NT; ++t)
; #pragma unroll
;         for (int s2 = 0; s2 < 2; ++s2) {
;             u32x4 pw; pw.x = cvt_pk_bf16(s[t][8 * s2 + 0], s[t][8 * s2 + 1]); pw.y = cvt_pk_bf16(s[t][8 * s2 + 2], s[t][8 * s2 + 3]);
;             pw.z = cvt_pk_bf16(s[t][8 * s2 + 4], s[t][8 * s2 + 5]); pw.w = cvt_pk_bf16(s[t][8 * s2 + 6], s[t][8 * s2 + 7]);
;             const bf16x8 pf = __builtin_bit_cast(bf16x8, pw);
; #pragma unroll
;             for (int d = 0; d < 2; ++d) {
;                 LAS const unsigned char* vp = vb + (t * 32 + s2 * 16) * 128 + ((d * 64) ^ vsw);
;                 const s16x4 lo = vtr(vp), hi4 = vtr(vp + 8 * 128);
;                 const bf16x8 vf = (bf16x8){lo[0], lo[1], lo[2], lo[3], hi4[0], hi4[1], hi4[2], hi4[3]};
;                 o[d] = __builtin_amdgcn_mfma_f32_32x32x16_bf16(vf, pf, o[d], 0, 0, 0);
;             }
;         }
	v_sub_f32_e32 v4, v43, v163
	v_add_f32_e32 v24, v48, v24
	v_add_f32_e32 v25, v49, v25
	v_add_f32_e32 v26, v50, v26
	v_add_f32_e32 v27, v51, v27
	v_exp_f32_e32 v43, v4
	v_sub_f32_e32 v4, v44, v163
	v_add_f32_e32 v0, v56, v24
	v_add_f32_e32 v1, v57, v25
	v_add_f32_e32 v2, v58, v26
	v_add_f32_e32 v3, v59, v27
	v_exp_f32_e32 v44, v4
	v_sub_f32_e32 v4, v45, v163
	v_add_f32_e32 v0, v60, v0
	v_add_f32_e32 v1, v61, v1
	v_add_f32_e32 v2, v62, v2
	v_add_f32_e32 v3, v63, v3
	v_exp_f32_e32 v45, v4
	v_sub_f32_e32 v4, v46, v163
	v_add_f32_e32 v0, v165, v0
	v_add_f32_e32 v1, v166, v1
	v_add_f32_e32 v2, v167, v2
	v_add_f32_e32 v3, v168, v3
	v_exp_f32_e32 v46, v4
	v_sub_f32_e32 v4, v47, v163
	v_add_f32_e32 v0, v183, v0
	v_add_f32_e32 v1, v185, v1
	v_add_f32_e32 v2, v186, v2
	v_add_f32_e32 v3, v187, v3
	v_exp_f32_e32 v47, v4
	v_add_f32_e32 v0, v188, v0
	v_add_f32_e32 v1, v189, v1
	v_add_f32_e32 v2, v190, v2
	v_add_f32_e32 v3, v191, v3
	v_add_f32_e32 v0, v192, v0
	v_add_f32_e32 v1, v193, v1
	v_add_f32_e32 v2, v194, v2
	v_add_f32_e32 v3, v195, v3
	v_add_f32_e32 v0, v40, v0
	v_add_f32_e32 v1, v41, v1
	v_add_f32_e32 v2, v42, v2
	v_add_f32_e32 v3, v43, v3
	ds_read_b64_tr_b16 v[4:5], v196 offset:49152
	ds_read_b64_tr_b16 v[6:7], v196 offset:50176
	v_add_f32_e32 v0, v44, v0
	v_add_f32_e32 v1, v45, v1
	v_add_f32_e32 v2, v46, v2
	v_add_f32_e32 v3, v47, v3
	v_add_f32_e32 v0, v1, v0
	v_add_f32_e32 v1, v2, v3
	v_add_f32_e32 v0, v1, v0
	v_add_f32_e32 v164, 0, v0
	v_cvt_pk_bf16_f32 v0, v16, v17
	v_cvt_pk_bf16_f32 v1, v18, v19
	v_cvt_pk_bf16_f32 v2, v20, v21
	v_cvt_pk_bf16_f32 v3, v22, v23
	v_cvt_pk_bf16_f32 v32, v52, v53
	v_cvt_pk_bf16_f32 v33, v54, v55
	s_waitcnt lgkmcnt(0)
	v_mfma_f32_32x32x16_bf16 v[16:31], v[4:7], v[0:3], 0
	ds_read_b64_tr_b16 v[4:5], v197 offset:49152
	ds_read_b64_tr_b16 v[6:7], v197 offset:50176
	ds_read_b64_tr_b16 v[36:37], v196 offset:51200
	ds_read_b64_tr_b16 v[38:39], v196 offset:52224
	v_cvt_pk_bf16_f32 v34, v48, v49
	v_cvt_pk_bf16_f32 v35, v50, v51
	s_waitcnt lgkmcnt(2)
	v_mfma_f32_32x32x16_bf16 v[0:15], v[4:7], v[0:3], 0
	s_waitcnt lgkmcnt(0)
	v_mfma_f32_32x32x16_bf16 v[16:31], v[36:39], v[32:35], v[16:31]
	ds_read_b64_tr_b16 v[36:37], v197 offset:51200
	ds_read_b64_tr_b16 v[38:39], v197 offset:52224
	s_waitcnt lgkmcnt(0)
	v_mfma_f32_32x32x16_bf16 v[0:15], v[36:39], v[32:35], v[0:15]
	ds_read_b64_tr_b16 v[36:37], v196 offset:53248
	ds_read_b64_tr_b16 v[38:39], v196 offset:54272
	ds_read_b64_tr_b16 v[198:199], v197 offset:53248
	ds_read_b64_tr_b16 v[200:201], v197 offset:54272
	v_cvt_pk_bf16_f32 v32, v56, v57
	v_cvt_pk_bf16_f32 v33, v58, v59
	v_cvt_pk_bf16_f32 v34, v60, v61
	v_cvt_pk_bf16_f32 v35, v62, v63
	s_waitcnt lgkmcnt(2)
	s_nop 0
	v_mfma_f32_32x32x16_bf16 v[16:31], v[36:39], v[32:35], v[16:31]
	s_waitcnt lgkmcnt(0)
	v_mfma_f32_32x32x16_bf16 v[0:15], v[198:201], v[32:35], v[0:15]
	ds_read_b64_tr_b16 v[36:37], v196 offset:55296
	ds_read_b64_tr_b16 v[38:39], v196 offset:56320
	ds_read_b64_tr_b16 v[198:199], v197 offset:55296
	ds_read_b64_tr_b16 v[200:201], v197 offset:56320
	v_cvt_pk_bf16_f32 v32, v165, v166
	v_cvt_pk_bf16_f32 v33, v167, v168
	v_cvt_pk_bf16_f32 v34, v183, v185
	v_cvt_pk_bf16_f32 v35, v186, v187
	v_add_u32_e32 v165, v147, v140
	s_waitcnt lgkmcnt(2)
	v_mfma_f32_32x32x16_bf16 v[16:31], v[36:39], v[32:35], v[16:31]
	s_waitcnt lgkmcnt(0)
	v_mfma_f32_32x32x16_bf16 v[0:15], v[198:201], v[32:35], v[0:15]
	ds_read_b64_tr_b16 v[36:37], v196 offset:57344
	ds_read_b64_tr_b16 v[38:39], v196 offset:58368
	ds_read_b64_tr_b16 v[198:199], v197 offset:57344
	ds_read_b64_tr_b16 v[200:201], v197 offset:58368
	v_cvt_pk_bf16_f32 v32, v188, v189
	v_cvt_pk_bf16_f32 v33, v190, v191
	v_cvt_pk_bf16_f32 v34, v192, v193
	v_cvt_pk_bf16_f32 v35, v194, v195
	s_waitcnt lgkmcnt(2)
	s_nop 0
	v_mfma_f32_32x32x16_bf16 v[16:31], v[36:39], v[32:35], v[16:31]
	s_waitcnt lgkmcnt(0)
	v_mfma_f32_32x32x16_bf16 v[0:15], v[198:201], v[32:35], v[0:15]
	ds_read_b64_tr_b16 v[36:37], v196 offset:59392
	ds_read_b64_tr_b16 v[38:39], v196 offset:60416
	ds_read_b64_tr_b16 v[198:199], v197 offset:59392
	ds_read_b64_tr_b16 v[200:201], v197 offset:60416
	v_cvt_pk_bf16_f32 v32, v40, v41
	v_cvt_pk_bf16_f32 v33, v42, v43
	v_cvt_pk_bf16_f32 v34, v44, v45
	v_cvt_pk_bf16_f32 v35, v46, v47
	s_waitcnt lgkmcnt(2)
	s_nop 0
	v_mfma_f32_32x32x16_bf16 v[16:31], v[36:39], v[32:35], v[16:31]
	s_waitcnt lgkmcnt(0)
	v_mfma_f32_32x32x16_bf16 v[0:15], v[198:201], v[32:35], v[0:15]
	v_add_u32_e32 v33, v147, v139
	ds_read_b128 v[50:53], v33
	ds_read_b128 v[186:189], v33 offset:4096
	v_cndmask_b32_e64 v32, 0, v227, s[6:7]
	v_mov_b32_e32 v33, v32
	v_mov_b32_e32 v34, v32
	v_mov_b32_e32 v35, v32
	v_mov_b32_e32 v36, v32
	v_mov_b32_e32 v37, v32
	v_mov_b32_e32 v38, v32
	v_mov_b32_e32 v39, v32
	v_mov_b32_e32 v40, v32
	v_mov_b32_e32 v41, v32
	v_mov_b32_e32 v42, v32
	v_mov_b32_e32 v43, v32
	v_mov_b32_e32 v44, v32
	v_mov_b32_e32 v45, v32
	v_mov_b32_e32 v46, v32
	v_mov_b32_e32 v47, v32
	v_cndmask_b32_e64 v48, 0, v32, s[70:71]
	v_mov_b32_e32 v49, v48
	s_waitcnt lgkmcnt(1)
	v_mfma_f32_32x32x16_bf16 v[32:47], v[50:53], v[124:127], v[32:47]
	v_mov_b32_e32 v50, v48
	v_mov_b32_e32 v51, v48
	v_mov_b32_e32 v52, v48
	v_mov_b32_e32 v53, v48
	v_mov_b32_e32 v54, v48
	v_mov_b32_e32 v55, v48
	v_mov_b32_e32 v56, v48
	v_mov_b32_e32 v57, v48
	v_mov_b32_e32 v58, v48
	v_mov_b32_e32 v59, v48
	v_mov_b32_e32 v60, v48
	v_mov_b32_e32 v61, v48
	v_mov_b32_e32 v62, v48
	v_mov_b32_e32 v63, v48
	v_readlane_b32 s6, v251, 59
	v_readlane_b32 s7, v251, 60
	s_waitcnt lgkmcnt(0)
	v_mfma_f32_32x32x16_bf16 v[48:63], v[186:189], v[124:127], v[48:63]
	ds_read_b128 v[124:127], v165
	ds_read_b128 v[186:189], v165 offset:4096
	s_add_u32 s2, s6, s2
	s_waitcnt lgkmcnt(1)
; __device__ __forceinline__ int crow(int i, int hi) { return (i & 3) + 8 * (i >> 2) + 4 * hi; }
; template <int T0, int NT, bool FIRST>
; __device__ __forceinline__ void attn_group(LAS const unsigned char* Kl, LAS const unsigned char* Vl, const bf16x8 (&qf)[4], f32x16 (&o)[2], float& mx, float& l, int nb, int w, int lane) {
;     ...
; #pragma unroll
;     for (int t = 0; t < NT; ++t) {
;         const int tt = T0 + t;
;         if (tt == 0) {
; #pragma unroll
;             for (int i = 0; i < 16; ++i) if (crow(i, hi) < r32) s[t][i] = NEGBIG; }
;         if (tt == 4) {
; #pragma unroll
;             for (int i = 0; i < 16; ++i) if (crow(i, hi) > r32) s[t][i] = NEGBIG; }
;     }
;     float m0 = s[0][0], m1 = s[0][1], m2 = s[0][2], m3 = s[0][3];
; #pragma unroll
;     for (int t = 0; t < NT; ++t)
; #pragma unroll
;         for (int i = 0; i < 16; i += 4) { m0 = fmaxf(m0, s[t][i]); m1 = fmaxf(m1, s[t][i + 1]); m2 = fmaxf(m2, s[t][i + 2]); m3 = fmaxf(m3, s[t][i + 3]); }
;     float gm = fmaxf(fmaxf(m0, m1), fmaxf(m2, m3));
;     gm = fmaxf(gm, __shfl_xor(gm, 32));
;     if (FIRST) mx = gm;
;     else { const float mn = fmaxf(mx, gm); const float f = __builtin_amdgcn_exp2f(mx - mn); l *= f; mx = mn;
; #pragma unroll
;         for (int d = 0; d < 2; ++d)
; #pragma unroll
;             for (int i = 0; i < 16; ++i) o[d][i] *= f; }
;     float l0 = 0.f, l1 = 0.f, l2 = 0.f, l3 = 0.f;
; #pragma unroll
;     for (int t = 0; t < NT; ++t)
; #pragma unroll
;         for (int i = 0; i < 16; i += 4) {
;             const float p0 = __builtin_amdgcn_exp2f(s[t][i] - mx), p1 = __builtin_amdgcn_exp2f(s[t][i + 1] - mx), p2 = __builtin_amdgcn_exp2f(s[t][i + 2] - mx), p3 = __builtin_amdgcn_exp2f(s[t][i + 3] - mx);
;             s[t][i] = p0; s[t][i + 1] = p1; s[t][i + 2] = p2; s[t][i + 3] = p3; l0 += p0; l1 += p1; l2 += p2; l3 += p3; }
	v_mfma_f32_32x32x16_bf16 v[32:47], v[124:127], v[120:123], v[32:47]
	v_add_u32_e32 v124, v147, v141
	s_waitcnt lgkmcnt(0)
	v_mfma_f32_32x32x16_bf16 v[48:63], v[186:189], v[120:123], v[48:63]
	ds_read_b128 v[120:123], v124
	ds_read_b128 v[124:127], v124 offset:4096
	s_waitcnt lgkmcnt(1)
	v_mfma_f32_32x32x16_bf16 v[32:47], v[120:123], v[116:119], v[32:47]
	v_add_u32_e32 v120, v147, v142
	s_waitcnt lgkmcnt(0)
	v_mfma_f32_32x32x16_bf16 v[48:63], v[124:127], v[116:119], v[48:63]
	ds_read_b128 v[116:119], v120
	ds_read_b128 v[120:123], v120 offset:4096
	s_waitcnt lgkmcnt(1)
	v_mfma_f32_32x32x16_bf16 v[32:47], v[116:119], v[112:115], v[32:47]
	s_waitcnt lgkmcnt(0)
	v_mfma_f32_32x32x16_bf16 v[48:63], v[120:123], v[112:115], v[48:63]
	s_nop 9
	v_cndmask_b32_e64 v32, v32, v227, s[40:41]
	v_cndmask_b32_e64 v36, v36, v227, s[94:95]
	v_cndmask_b32_e64 v33, v33, v227, s[0:1]
	v_cndmask_b32_e64 v112, v34, v227, s[38:39]
	v_cndmask_b32_e64 v37, v37, v227, s[92:93]
	v_cndmask_b32_e64 v113, v44, v227, s[54:55]
	v_max_f32_e32 v34, v36, v36
	v_max_f32_e32 v44, v32, v32
	v_cndmask_b32_e64 v35, v35, v227, s[96:97]
	v_cndmask_b32_e64 v39, v39, v227, s[88:89]
	v_max_f32_e32 v34, v44, v34
	v_max_f32_e32 v44, v37, v37
	v_max_f32_e32 v114, v33, v33
	v_max_f32_e32 v44, v114, v44
	v_max_f32_e32 v114, v39, v39
	v_max_f32_e32 v115, v35, v35
	v_cndmask_b32_e64 v38, v38, v227, s[90:91]
	v_cndmask_b32_e64 v42, v42, v227, s[58:59]
	v_cndmask_b32_e64 v43, v43, v227, s[56:57]
	v_cndmask_b32_e64 v47, v47, v227, s[76:77]
	v_max_f32_e32 v114, v115, v114
	v_cndmask_b32_e64 v40, v40, v227, s[62:63]
	v_cndmask_b32_e64 v41, v41, v227, s[60:61]
	v_cndmask_b32_e64 v45, v45, v227, s[52:53]
	v_cndmask_b32_e64 v46, v46, v227, s[50:51]
	v_max3_f32 v115, v112, v38, v42
	v_max3_f32 v114, v114, v43, v47
	v_max3_f32 v34, v34, v40, v113
	v_max3_f32 v44, v44, v41, v45
	v_max3_f32 v115, v115, v46, v50
	v_max3_f32 v114, v114, v51, v55
	v_max3_f32 v34, v34, v48, v52
	v_max3_f32 v44, v44, v49, v53
	v_max3_f32 v115, v115, v54, v58
	v_max3_f32 v114, v114, v59, v63
	v_max3_f32 v34, v34, v56, v60
	v_max3_f32 v44, v44, v57, v61
	v_max3_f32 v114, v115, v62, v114
	v_max3_f32 v34, v34, v44, v114
	ds_bpermute_b32 v44, v150, v34
	s_waitcnt lgkmcnt(0)
	v_max3_f32 v34, v163, v34, v44
	v_sub_f32_e32 v32, v32, v34
	v_exp_f32_e32 v114, v32
	v_sub_f32_e32 v32, v33, v34
	v_sub_f32_e32 v36, v36, v34
	v_exp_f32_e32 v33, v32
	v_sub_f32_e32 v32, v112, v34
	v_exp_f32_e32 v118, v36
	v_sub_f32_e32 v36, v37, v34
	v_exp_f32_e32 v112, v32
	v_sub_f32_e32 v32, v35, v34
	v_exp_f32_e32 v119, v36
	v_sub_f32_e32 v36, v38, v34
	v_exp_f32_e32 v35, v32
	v_exp_f32_e32 v120, v36
	v_sub_f32_e32 v36, v39, v34
	v_exp_f32_e32 v39, v36
	v_add_f32_e32 v115, 0, v33
	v_sub_f32_e32 v40, v40, v34
	v_add_f32_e32 v116, 0, v112
	v_add_f32_e32 v36, v119, v115
	v_exp_f32_e32 v115, v40
	v_sub_f32_e32 v40, v41, v34
	v_add_f32_e32 v117, 0, v35
	v_add_f32_e32 v37, v120, v116
	v_exp_f32_e32 v116, v40
	v_sub_f32_e32 v40, v42, v34
	v_add_f32_e32 v38, v39, v117
	v_exp_f32_e32 v117, v40
	v_sub_f32_e32 v40, v43, v34
	v_exp_f32_e32 v121, v40
	v_sub_f32_e32 v40, v113, v34
	v_exp_f32_e32 v113, v40
	v_sub_f32_e32 v40, v45, v34
	v_exp_f32_e32 v45, v40
	v_sub_f32_e32 v40, v46, v34
	v_exp_f32_e32 v46, v40
	v_sub_f32_e32 v40, v47, v34
	v_exp_f32_e32 v47, v40
	v_sub_f32_e32 v40, v48, v34
	v_exp_f32_e32 v48, v40
	v_sub_f32_e32 v40, v49, v34
	v_exp_f32_e32 v49, v40
	v_sub_f32_e32 v40, v50, v34
	v_exp_f32_e32 v50, v40
	v_sub_f32_e32 v40, v51, v34
	v_exp_f32_e32 v51, v40
	v_sub_f32_e32 v40, v52, v34
	v_exp_f32_e32 v52, v40
	v_sub_f32_e32 v40, v53, v34
	v_exp_f32_e32 v53, v40
	v_sub_f32_e32 v40, v54, v34
	v_exp_f32_e32 v54, v40
	v_sub_f32_e32 v40, v55, v34
	v_exp_f32_e32 v55, v40
	v_sub_f32_e32 v40, v56, v34
	v_exp_f32_e32 v56, v40
	v_sub_f32_e32 v40, v57, v34
	v_exp_f32_e32 v57, v40
	v_sub_f32_e32 v40, v58, v34
	v_exp_f32_e32 v58, v40
	v_sub_f32_e32 v40, v59, v34
	v_exp_f32_e32 v59, v40
	v_sub_f32_e32 v40, v60, v34
	v_add_f32_e32 v32, 0, v114
	v_exp_f32_e32 v60, v40
	v_sub_f32_e32 v40, v61, v34
	v_add_f32_e32 v32, v118, v32
	v_exp_f32_e32 v61, v40
	v_sub_f32_e32 v40, v62, v34
	v_add_f32_e32 v32, v115, v32
	v_add_f32_e32 v36, v116, v36
	v_add_f32_e32 v37, v117, v37
	v_add_f32_e32 v38, v121, v38
	v_exp_f32_e32 v62, v40
	v_sub_f32_e32 v40, v63, v34
	v_add_f32_e32 v32, v113, v32
	v_add_f32_e32 v36, v45, v36
	v_add_f32_e32 v37, v46, v37
	v_add_f32_e32 v38, v47, v38
	v_exp_f32_e32 v63, v40
	v_add_f32_e32 v32, v48, v32
	v_add_f32_e32 v36, v49, v36
	v_add_f32_e32 v37, v50, v37
	v_add_f32_e32 v38, v51, v38
	v_add_f32_e32 v32, v52, v32
	v_add_f32_e32 v36, v53, v36
	v_add_f32_e32 v37, v54, v37
	v_add_f32_e32 v38, v55, v38
	v_add_f32_e32 v32, v56, v32
	v_add_f32_e32 v36, v57, v36
	v_add_f32_e32 v37, v58, v37
	v_add_f32_e32 v38, v59, v38
	v_add_f32_e32 v32, v60, v32
	v_add_f32_e32 v36, v61, v36
	v_add_f32_e32 v37, v62, v37
	v_add_f32_e32 v38, v63, v38
	v_add_f32_e32 v32, v32, v36
	v_add_f32_e32 v36, v37, v38
	v_sub_f32_e32 v44, v163, v34
	v_add_f32_e32 v32, v32, v36
	v_cvt_pk_bf16_f32 v36, v114, v33
	v_add_u32_e32 v33, v148, v144
	v_exp_f32_e32 v44, v44
	ds_read_b64_tr_b16 v[40:41], v33 offset:49152
	ds_read_b64_tr_b16 v[42:43], v33 offset:50176
	v_cvt_pk_bf16_f32 v37, v112, v35
	v_cvt_pk_bf16_f32 v38, v118, v119
	v_cvt_pk_bf16_f32 v39, v120, v39
	v_pk_mul_f32 v[30:31], v[30:31], v[44:45] op_sel_hi:[1,0]
	v_pk_mul_f32 v[28:29], v[28:29], v[44:45] op_sel_hi:[1,0]
	v_pk_mul_f32 v[26:27], v[26:27], v[44:45] op_sel_hi:[1,0]
	v_pk_mul_f32 v[24:25], v[24:25], v[44:45] op_sel_hi:[1,0]
	v_pk_mul_f32 v[22:23], v[22:23], v[44:45] op_sel_hi:[1,0]
	v_pk_mul_f32 v[20:21], v[20:21], v[44:45] op_sel_hi:[1,0]
	v_pk_mul_f32 v[18:19], v[18:19], v[44:45] op_sel_hi:[1,0]
	v_pk_mul_f32 v[16:17], v[16:17], v[44:45] op_sel_hi:[1,0]
	v_add_u32_e32 v35, v148, v145
	v_pk_mul_f32 v[14:15], v[14:15], v[44:45] op_sel_hi:[1,0]
	s_waitcnt lgkmcnt(0)
; #define LAS __attribute__((address_space(3)))
; __device__ __forceinline__ s16x4 vtr(LAS const unsigned char* p) { return __builtin_bit_cast(s16x4, __builtin_amdgcn_ds_read_tr16_b64_v4i16((LAS v4i16_t*)p)); }
; template <int T0, int NT, bool FIRST>
; __device__ __forceinline__ void attn_group(LAS const unsigned char* Kl, LAS const unsigned char* Vl, const bf16x8 (&qf)[4], f32x16 (&o)[2], float& mx, float& l, int nb, int w, int lane) {
;     ...
;     const int i16 = lane & 15, q4 = i16 >> 2, p4 = i16 & 3, blk = (lane >> 4) & 1;
;     LAS const unsigned char* vb = Vl + (32 * (w + T0) + 4 * hi + q4) * 128 + 32 * blk + 8 * p4;
;     const int vsw = ((q4 >> 1) & 1) * 64;
; #pragma unroll
;     for (int t = 0; t < NT; ++t)
; #pragma unroll
;         for (int s2 = 0; s2 < 2; ++s2) {
;             u32x4 pw; pw.x = cvt_pk_bf16(s[t][8 * s2 + 0], s[t][8 * s2 + 1]); pw.y = cvt_pk_bf16(s[t][8 * s2 + 2], s[t][8 * s2 + 3]);
;             pw.z = cvt_pk_bf16(s[t][8 * s2 + 4], s[t][8 * s2 + 5]); pw.w = cvt_pk_bf16(s[t][8 * s2 + 6], s[t][8 * s2 + 7]);
;             const bf16x8 pf = __builtin_bit_cast(bf16x8, pw);
; #pragma unroll
;             for (int d = 0; d < 2; ++d) {
;                 LAS const unsigned char* vp = vb + (t * 32 + s2 * 16) * 128 + ((d * 64) ^ vsw);
;                 const s16x4 lo = vtr(vp), hi4 = vtr(vp + 8 * 128);
;                 const bf16x8 vf = (bf16x8){lo[0], lo[1], lo[2], lo[3], hi4[0], hi4[1], hi4[2], hi4[3]};
;                 o[d] = __builtin_amdgcn_mfma_f32_32x32x16_bf16(vf, pf, o[d], 0, 0, 0);
;             }
;         }
; template <bool FINAL>
; __device__ __forceinline__ void attn_compute(LAS unsigned char* lds, const bf16_t* proj, const AttnItem& t, const AttnItem& nxt, bool more, bf16x8 (&qf)[4], bf16_t* o23, float* lse23, bf16_t* ycat, int lane, int wid) {
;     ...
;     l += __shfl_xor(l, 32);
;     attn_load_q(proj, nxt, qf, lane, wid);
;     const float lse = mx + __builtin_amdgcn_logf(l);
;     if (!FINAL) {
;         const float c1 = 1.0f / l;
;         if (hi == 0) lse23[(size_t)t.br * M * NH + hrow] = lse;
	v_mfma_f32_32x32x16_bf16 v[16:31], v[40:43], v[36:39], v[16:31]
	ds_read_b64_tr_b16 v[40:41], v35 offset:49152
	ds_read_b64_tr_b16 v[42:43], v35 offset:50176
	v_mul_f32_e64 v12, v12, v44
	v_mul_f32_e64 v13, v13, v44
	v_mul_f32_e64 v10, v10, v44
	v_mul_f32_e64 v11, v11, v44
	v_pk_mul_f32 v[8:9], v[8:9], v[44:45] op_sel_hi:[1,0]
	v_pk_mul_f32 v[6:7], v[6:7], v[44:45] op_sel_hi:[1,0]
	v_pk_mul_f32 v[4:5], v[4:5], v[44:45] op_sel_hi:[1,0]
	v_pk_mul_f32 v[2:3], v[2:3], v[44:45] op_sel_hi:[1,0]
	v_pk_mul_f32 v[0:1], v[0:1], v[44:45] op_sel_hi:[1,0]
	v_fmac_f32_e32 v32, v164, v44
	s_waitcnt lgkmcnt(0)
	v_mfma_f32_32x32x16_bf16 v[0:15], v[40:43], v[36:39], v[0:15]
	ds_read_b64_tr_b16 v[40:41], v33 offset:51200
	ds_read_b64_tr_b16 v[42:43], v33 offset:52224
	ds_read_b64_tr_b16 v[198:199], v35 offset:51200
	ds_read_b64_tr_b16 v[200:201], v35 offset:52224
	v_cvt_pk_bf16_f32 v36, v115, v116
	v_cvt_pk_bf16_f32 v37, v117, v121
	v_cvt_pk_bf16_f32 v38, v113, v45
	v_cvt_pk_bf16_f32 v39, v46, v47
	s_waitcnt lgkmcnt(2)
	s_nop 0
	v_mfma_f32_32x32x16_bf16 v[16:31], v[40:43], v[36:39], v[16:31]
	s_waitcnt lgkmcnt(0)
	v_mfma_f32_32x32x16_bf16 v[0:15], v[198:201], v[36:39], v[0:15]
	ds_read_b64_tr_b16 v[40:41], v33 offset:53248
	ds_read_b64_tr_b16 v[42:43], v33 offset:54272
	ds_read_b64_tr_b16 v[198:199], v35 offset:53248
	ds_read_b64_tr_b16 v[200:201], v35 offset:54272
	v_cvt_pk_bf16_f32 v36, v48, v49
	v_cvt_pk_bf16_f32 v37, v50, v51
	v_cvt_pk_bf16_f32 v38, v52, v53
	v_cvt_pk_bf16_f32 v39, v54, v55
	s_waitcnt lgkmcnt(2)
	s_nop 0
	v_mfma_f32_32x32x16_bf16 v[16:31], v[40:43], v[36:39], v[16:31]
	s_waitcnt lgkmcnt(0)
	v_mfma_f32_32x32x16_bf16 v[0:15], v[198:201], v[36:39], v[0:15]
	ds_read_b64_tr_b16 v[40:41], v33 offset:55296
	ds_read_b64_tr_b16 v[42:43], v33 offset:56320
	v_cvt_pk_bf16_f32 v36, v56, v57
	v_cvt_pk_bf16_f32 v37, v58, v59
	v_cvt_pk_bf16_f32 v38, v60, v61
	v_cvt_pk_bf16_f32 v39, v62, v63
	ds_bpermute_b32 v33, v150, v32
	s_waitcnt lgkmcnt(1)
	v_mfma_f32_32x32x16_bf16 v[16:31], v[40:43], v[36:39], v[16:31]
	ds_read_b64_tr_b16 v[40:41], v35 offset:55296
	ds_read_b64_tr_b16 v[42:43], v35 offset:56320
	v_or_b32_e32 v35, s49, v149
	v_lshlrev_b32_e32 v35, s3, v35
	v_add_u32_e32 v35, s98, v35
	s_addc_u32 s3, s7, 0
	s_waitcnt lgkmcnt(0)
	v_mfma_f32_32x32x16_bf16 v[0:15], v[40:43], v[36:39], v[0:15]
	v_lshlrev_b32_e32 v37, 7, v35
	v_and_b32_e32 v36, 0x3f800, v35
	v_and_b32_e32 v37, 0x780, v37
	v_bfe_u32 v35, v35, 4, 7
	v_or3_b32 v35, v37, v36, v35
	v_lshlrev_b32_e32 v168, 7, v35
	v_lshl_add_u64 v[36:37], s[2:3], 0, v[168:169]
	v_lshl_add_u64 v[36:37], v[128:129], 1, v[36:37]
	global_load_dwordx4 v[124:127], v[36:37], off
	global_load_dwordx4 v[120:123], v[36:37], off offset:32
	global_load_dwordx4 v[116:119], v[36:37], off offset:64
	global_load_dwordx4 v[112:115], v[36:37], off offset:96
	s_and_saveexec_b64 s[2:3], s[4:5]
	s_xor_b64 s[2:3], exec, s[2:3]
	s_ashr_i32 s49, s48, 31
	s_or_saveexec_b64 s[2:3], s[2:3]
	v_lshl_or_b32 v35, s25, 7, v146
	v_mov_b32_e32 v36, s24
	v_mad_i32_i24 v35, s20, v35, v36
	v_lshlrev_b32_e32 v37, 7, v35
	v_and_b32_e32 v36, 0xfffff800, v35
	v_and_b32_e32 v37, 0x780, v37
	v_bfe_u32 v35, v35, 4, 7
	s_lshl_b32 s6, s23, 16
	s_lshl_b32 s7, s22, 13
	v_or3_b32 v35, v37, v36, v35
	s_or_b32 s6, s6, s7
	v_add_u32_e32 v168, s6, v35
	v_add_f32_e32 v35, v32, v33
	v_mov_b64_e32 v[32:33], s[48:49]
	s_xor_b64 exec, exec, s[2:3]
	s_cbranch_execz .LBB0_107
	v_log_f32_e32 v32, v35
	s_ashr_i32 s49, s48, 31
	s_lshl_b64 s[6:7], s[48:49], 20
	v_readlane_b32 s22, v251, 61
	v_readlane_b32 s23, v251, 62
	s_add_u32 s6, s22, s6
	s_addc_u32 s7, s23, s7
	v_add_f32_e32 v34, v34, v32
	v_lshl_add_u64 v[32:33], v[168:169], 2, s[6:7]
	global_store_dword v[32:33], v34, off
	v_mov_b64_e32 v[32:33], s[48:49]
	s_branch .LBB0_107
